# G1-even: second-round tile takes pn^4 (one GELU + one GLU epilogue per workgroup instead of two of a kind), on stack12
# speedup vs baseline: 1.0106x; 1.0026x over previous
;     __host__ __device__ bool next(int i, Unit& u) const {
;         const long L = (long)i * G + c; if (L >= nwg) return false;
;         int wgid = (int)L; { const int q = nwg / NXCD, r = nwg % NXCD, xcd = wgid % NXCD, off = wgid / NXCD; wgid = (xcd < r ? xcd * (q + 1) : r * (q + 1) + (xcd - r) * q) + off; }
;         const int nig = wgm * nN, gid = wgid / nig, fm = gid * wgm, gsz = (nM - fm) < wgm ? (nM - fm) : wgm;
;         u.pm = fm + ((wgid % nig) % gsz); u.pn = (wgid % nig) / gsz; return true;
.LBB0_263:
	s_ashr_i32 s11, s11, 3
	s_add_i32 s11, s20, s11
	s_ashr_i32 s14, s11, 31
	s_lshr_b32 s14, s14, 28
	s_add_i32 s14, s11, s14
	s_ashr_i32 s20, s14, 4
	s_lshl_b32 s20, s20, 1
	s_sub_i32 s21, 64, s20
	s_min_i32 s21, s21, 2
	s_abs_i32 s22, s21
	v_cvt_f32_u32_e32 v0, s22
	s_sub_i32 s24, 0, s22
	s_and_b32 s14, s14, -16
	s_sub_i32 s11, s11, s14
	v_rcp_iflag_f32_e32 v0, v0
	s_abs_i32 s14, s11
	s_xor_b32 s23, s11, s21
	s_ashr_i32 s23, s23, 31
	v_mul_f32_e32 v0, 0x4f7ffffe, v0
	v_cvt_u32_f32_e32 v0, v0
	s_nop 0
	v_readfirstlane_b32 s25, v0
	s_mul_i32 s24, s24, s25
	s_mul_hi_u32 s24, s25, s24
	s_add_i32 s25, s25, s24
	s_mul_hi_u32 s24, s14, s25
	s_mul_i32 s25, s24, s22
	s_sub_i32 s14, s14, s25
	s_add_i32 s26, s24, 1
	s_sub_i32 s25, s14, s22
	s_cmp_ge_u32 s14, s22
	s_cselect_b32 s24, s26, s24
	s_cselect_b32 s14, s25, s14
	s_add_i32 s25, s24, 1
	s_cmp_ge_u32 s14, s22
	s_cselect_b32 s14, s25, s24
	s_xor_b32 s14, s14, s23
	s_sub_i32 s46, s14, s23
	s_mul_i32 s14, s46, s21
	s_sub_i32 s11, s11, s14
	s_add_i32 s48, s20, s11
	v_readlane_b32 s98, v252, 10
	s_cmp_eq_u32 s98, 0x100
	s_cselect_b32 s98, 4, 0
	s_bitcmp1_b32 s63, 0
	s_cselect_b32 s98, s98, 0
	s_xor_b32 s46, s46, s98
